# NA attention: bias+window mask vectorised (16 ds_read2_b32 + add + cndmask with precomputed masks instead of 32 exec-masked serial LDS reads)
# speedup vs baseline: 1.0279x; 1.0081x over previous
.LBB0_751:
	v_lshl_add_u64 v[54:55], vcc, 0, v[192:193]
	v_mad_i64_i32 v[50:51], vcc, s96, v188, 0
	v_lshl_add_u64 v[50:51], v[50:51], 1, v[48:49]
	v_lshl_add_u64 v[50:51], v[164:165], 1, v[50:51]
	flat_load_dwordx4 v[148:151], v[50:51]
	v_mad_i64_i32 v[50:51], vcc, s94, v166, 0
	v_lshl_add_u64 v[50:51], v[50:51], 1, v[54:55]
	flat_load_dwordx4 v[144:147], v[50:51]
	v_mad_i64_i32 v[50:51], vcc, s96, v189, 0
	v_lshl_add_u64 v[50:51], v[50:51], 1, v[48:49]
	v_lshl_add_u64 v[50:51], v[168:169], 1, v[50:51]
	flat_load_dwordx4 v[140:143], v[50:51]
	v_mad_i64_i32 v[50:51], vcc, s94, v170, 0
	v_lshl_add_u64 v[50:51], v[50:51], 1, v[54:55]
	flat_load_dwordx4 v[132:135], v[50:51]
	v_mad_i64_i32 v[50:51], vcc, s96, v190, 0
	v_mad_i64_i32 v[56:57], s[96:97], s96, v191, 0
	v_lshl_add_u64 v[50:51], v[50:51], 1, v[48:49]
	v_lshl_add_u64 v[48:49], v[56:57], 1, v[48:49]
	v_lshl_add_u64 v[50:51], v[172:173], 1, v[50:51]
	v_lshl_add_u64 v[48:49], v[176:177], 1, v[48:49]
	flat_load_dwordx4 v[136:139], v[50:51]
	flat_load_dwordx4 v[156:159], v[48:49]
	v_mad_i64_i32 v[50:51], vcc, s94, v174, 0
	v_mad_i64_i32 v[48:49], s[94:95], s94, v178, 0
	v_lshl_add_u64 v[50:51], v[50:51], 1, v[54:55]
	v_lshl_add_u64 v[48:49], v[48:49], 1, v[54:55]
	flat_load_dwordx4 v[128:131], v[50:51]
	flat_load_dwordx4 v[152:155], v[48:49]
	s_mul_i32 s47, s47, 0x8400
	v_add_u32_e32 v84, s47, v171
	ds_read_b128 v[50:53], v84
	ds_read_b128 v[80:83], v84 offset:16896
	s_waitcnt lgkmcnt(0)
	v_mfma_f32_32x32x16_bf16 v[64:79], v[50:53], v[124:127], v[32:47]
	s_cmp_gt_u32 s46, 7
	v_mfma_f32_32x32x16_bf16 v[48:63], v[80:83], v[124:127], v[32:47]
	ds_read_b128 v[80:83], v84 offset:32
	s_waitcnt lgkmcnt(0)
	v_mfma_f32_32x32x16_bf16 v[64:79], v[80:83], v[120:123], v[64:79]
	ds_read_b128 v[80:83], v84 offset:16928
	s_waitcnt lgkmcnt(0)
	v_mfma_f32_32x32x16_bf16 v[48:63], v[80:83], v[120:123], v[48:63]
	ds_read_b128 v[80:83], v84 offset:64
	s_waitcnt lgkmcnt(0)
	v_mfma_f32_32x32x16_bf16 v[64:79], v[80:83], v[116:119], v[64:79]
	ds_read_b128 v[80:83], v84 offset:16960
	s_waitcnt lgkmcnt(0)
	v_mfma_f32_32x32x16_bf16 v[48:63], v[80:83], v[116:119], v[48:63]
	ds_read_b128 v[80:83], v84 offset:96
	s_waitcnt lgkmcnt(0)
	v_mfma_f32_32x32x16_bf16 v[64:79], v[80:83], v[112:115], v[64:79]
	ds_read_b128 v[80:83], v84 offset:16992
	s_waitcnt lgkmcnt(0)
	v_mfma_f32_32x32x16_bf16 v[48:63], v[80:83], v[112:115], v[48:63]
	s_cbranch_scc1 .LBB0_817
	v_add_u32_e32 v229, s90, v228
	v_add_u32_e32 v229, 0x23268, v229
	ds_read2_b32 v[80:81], v229 offset0:32 offset1:33
	ds_read2_b32 v[82:83], v229 offset0:34 offset1:35
	ds_read2_b32 v[84:85], v229 offset0:40 offset1:41
	ds_read2_b32 v[86:87], v229 offset0:42 offset1:43
	ds_read2_b32 v[88:89], v229 offset0:48 offset1:49
	ds_read2_b32 v[90:91], v229 offset0:50 offset1:51
	ds_read2_b32 v[92:93], v229 offset0:56 offset1:57
	ds_read2_b32 v[94:95], v229 offset0:58 offset1:59
	ds_read2_b32 v[96:97], v229 offset0:0 offset1:1
	ds_read2_b32 v[98:99], v229 offset0:2 offset1:3
	ds_read2_b32 v[100:101], v229 offset0:8 offset1:9
	ds_read2_b32 v[102:103], v229 offset0:10 offset1:11
	ds_read2_b32 v[104:105], v229 offset0:16 offset1:17
	ds_read2_b32 v[106:107], v229 offset0:18 offset1:19
	ds_read2_b32 v[108:109], v229 offset0:24 offset1:25
	ds_read2_b32 v[110:111], v229 offset0:26 offset1:27
	v_mov_b32_e32 v230, 0xff800000
	s_waitcnt lgkmcnt(8)
	v_add_f32_e32 v48, v48, v80
	v_cndmask_b32_e64 v48, v230, v48, s[4:5]
	v_add_f32_e32 v49, v49, v81
	v_cndmask_b32_e64 v49, v230, v49, s[42:43]
	v_add_f32_e32 v50, v50, v82
	v_cndmask_b32_e64 v50, v230, v50, s[44:45]
	v_add_f32_e32 v51, v51, v83
	v_cndmask_b32_e64 v51, v230, v51, s[48:49]
	v_add_f32_e32 v52, v52, v84
	v_cndmask_b32_e64 v52, v230, v52, s[50:51]
	v_add_f32_e32 v53, v53, v85
	v_cndmask_b32_e64 v53, v230, v53, s[52:53]
	v_add_f32_e32 v54, v54, v86
	v_cndmask_b32_e64 v54, v230, v54, s[54:55]
	v_add_f32_e32 v55, v55, v87
	v_cndmask_b32_e64 v55, v230, v55, s[58:59]
	v_add_f32_e32 v56, v56, v88
	v_cndmask_b32_e64 v56, v230, v56, s[22:23]
	v_add_f32_e32 v57, v57, v89
	v_cndmask_b32_e64 v57, v230, v57, s[24:25]
	v_add_f32_e32 v58, v58, v90
	v_cndmask_b32_e64 v58, v230, v58, s[26:27]
	v_add_f32_e32 v59, v59, v91
	v_cndmask_b32_e64 v59, v230, v59, s[28:29]
	v_add_f32_e32 v60, v60, v92
	v_cndmask_b32_e64 v60, v230, v60, s[30:31]
	v_add_f32_e32 v61, v61, v93
	v_cndmask_b32_e64 v61, v230, v61, s[34:35]
	v_add_f32_e32 v62, v62, v94
	v_cndmask_b32_e64 v62, v230, v62, s[36:37]
	v_add_f32_e32 v63, v63, v95
	v_cndmask_b32_e64 v63, v230, v63, s[38:39]
	s_waitcnt lgkmcnt(0)
	v_add_f32_e32 v64, v64, v96
	v_cndmask_b32_e64 v64, v230, v64, s[6:7]
	v_add_f32_e32 v65, v65, v97
	v_cndmask_b32_e64 v65, v230, v65, s[8:9]
	v_add_f32_e32 v66, v66, v98
	v_cndmask_b32_e64 v66, v230, v66, s[10:11]
	v_add_f32_e32 v67, v67, v99
	v_cndmask_b32_e64 v67, v230, v67, s[12:13]
	v_add_f32_e32 v68, v68, v100
	v_cndmask_b32_e64 v68, v230, v68, s[14:15]
	v_add_f32_e32 v69, v69, v101
	v_cndmask_b32_e64 v69, v230, v69, s[16:17]
	v_add_f32_e32 v70, v70, v102
	v_cndmask_b32_e64 v70, v230, v70, s[18:19]
	v_add_f32_e32 v71, v71, v103
	v_cndmask_b32_e64 v71, v230, v71, s[20:21]
	v_add_f32_e32 v72, v72, v104
	v_cndmask_b32_e64 v72, v230, v72, s[60:61]
	v_add_f32_e32 v73, v73, v105
	v_cndmask_b32_e64 v73, v230, v73, s[62:63]
	v_add_f32_e32 v74, v74, v106
	v_cndmask_b32_e64 v74, v230, v74, s[68:69]
	v_add_f32_e32 v75, v75, v107
	v_cndmask_b32_e64 v75, v230, v75, s[70:71]
	v_add_f32_e32 v76, v76, v108
	v_cndmask_b32_e64 v76, v230, v76, s[72:73]
	v_add_f32_e32 v77, v77, v109
	v_cndmask_b32_e64 v77, v230, v77, s[80:81]
	v_add_f32_e32 v78, v78, v110
	v_cndmask_b32_e64 v78, v230, v78, s[82:83]
	v_add_f32_e32 v79, v79, v111
	v_cndmask_b32_e64 v79, v230, v79, s[84:85]
